# rownorm passes: the in-loop s_waitcnt vmcnt(1)/(0) that guarded the once-loaded gain registers (and drained the next-row prefetch mid-iteration) moved to the prologue; prefetched row now waited only a
# speedup vs baseline: 1.0003x; 1.0003x over previous
; __device__ __forceinline__ void rownorm_pass(int lane, int gw, int NGW, bf16* XB, const bf16* MB, const float* gpost, float* RS, float* OUT) {
;     f32x4 gp[4];
; #pragma unroll
;     for (int j = 0; j < 4; ++j) gp[j] = *(const f32x4*)(gpost + 4 * lane + 256 * j);
;     v2u nx[4], nm[4];
;     int row = gw;
;     if (row < MTOK) {
; #pragma unroll
;         for (int j = 0; j < 4; ++j) { nx[j] = *(const v2u*)(XB + (size_t)row * DMODEL + 4 * lane + 256 * j); nm[j] = __builtin_nontemporal_load((const v2u*)(MB + (size_t)row * DMODEL + 4 * lane + 256 * j)); }
;     }
;     while (row < MTOK) {
;         v2u xw[4], w[4];
; #pragma unroll
;         for (int j = 0; j < 4; ++j) { xw[j] = nx[j]; w[j] = nm[j]; }
;         const int nrow = row + NGW;
;         if (nrow < MTOK) {
; #pragma unroll
;             for (int j = 0; j < 4; ++j) { nx[j] = *(const v2u*)(XB + (size_t)nrow * DMODEL + 4 * lane + 256 * j); nm[j] = __builtin_nontemporal_load((const v2u*)(MB + (size_t)nrow * DMODEL + 4 * lane + 256 * j)); }
;         }
.LBB0_660:
	v_readlane_b32 s12, v255, 3
	s_ashr_i32 s3, s1, 6
	s_lshl_b32 s2, s2, 3
	v_readlane_b32 s6, v255, 9
	v_readlane_b32 s13, v255, 4
	s_lshl_b32 s12, s14, 10
	s_add_i32 s8, s2, s3
	v_readlane_b32 s7, v255, 10
	v_writelane_b32 v255, s12, 3
	s_cmp_gt_i32 s8, 0x13fff
	s_load_dwordx2 s[10:11], s[6:7], 0x80
	s_waitcnt lgkmcnt(0)
	s_load_dwordx2 s[6:7], s[6:7], 0x60
	s_waitcnt lgkmcnt(0)
	s_nop 0
	v_writelane_b32 v255, s13, 4
	s_cbranch_scc1 .LBB0_667
	s_lshl_b32 s72, s0, 3
	v_readlane_b32 s0, v255, 3
	v_readlane_b32 s1, v255, 4
	s_lshl_b64 s[0:1], s[0:1], 2
	s_add_u32 s0, s6, s0
	s_addc_u32 s1, s7, s1
	s_ashr_i32 s9, s8, 31
	s_lshl_b64 s[12:13], s[8:9], 11
	v_and_b32_e32 v1, 63, v1
	s_add_u32 s6, s10, s12
	s_addc_u32 s7, s11, s13
	v_lshlrev_b32_e32 v20, 3, v1
	v_mov_b32_e32 v21, v0
	v_lshl_add_u64 v[10:11], s[6:7], 0, v[20:21]
	s_mov_b64 s[6:7], 0xfa00000
	v_lshl_add_u64 v[12:13], v[10:11], 0, s[6:7]
	s_mov_b32 s6, 0x35200000
	v_add_co_u32_e32 v2, vcc, s6, v10
	s_mov_b32 s6, 0xfa00000
	s_nop 0
	v_addc_co_u32_e32 v3, vcc, 0, v11, vcc
	v_add_co_u32_e32 v4, vcc, s6, v10
	v_lshlrev_b32_e32 v14, 4, v1
	s_nop 0
	v_addc_co_u32_e32 v5, vcc, 0, v11, vcc
	global_load_dwordx2 v[48:49], v[2:3], off
	global_load_dwordx2 v[52:53], v[4:5], off nt
	global_load_dwordx2 v[46:47], v[12:13], off offset:1024 nt
	global_load_dwordx2 v[44:45], v[12:13], off offset:1536 nt
	s_nop 0
	global_load_dwordx4 v[2:5], v14, s[0:1]
	global_load_dwordx4 v[6:9], v14, s[0:1] offset:1024
	global_load_dwordx2 v[50:51], v[12:13], off offset:512 nt
	s_mov_b64 s[6:7], 0x35200000
	v_lshl_add_u64 v[10:11], v[10:11], 0, s[6:7]
	global_load_dwordx2 v[42:43], v[10:11], off offset:512
	global_load_dwordx2 v[40:41], v[10:11], off offset:1024
	global_load_dwordx2 v[38:39], v[10:11], off offset:1536
	s_nop 0
	global_load_dwordx4 v[10:13], v14, s[0:1] offset:2048
	s_nop 0
	global_load_dwordx4 v[14:17], v14, s[0:1] offset:3072
	s_lshl_b64 s[0:1], s[8:9], 2
	s_add_u32 s0, s0, 0xa0000
	s_addc_u32 s1, s1, 0
	s_add_i32 s3, s3, s72
	s_add_i32 s2, s3, s2
	s_ashr_i32 s3, s2, 31
	v_lshlrev_b32_e32 v18, 2, v1
	s_ashr_i32 s73, s72, 31
	s_lshl_b64 s[2:3], s[2:3], 11
	v_cmp_eq_u32_e64 s[6:7], 0, v1
	v_xor_b32_e32 v1, 64, v18
	v_xor_b32_e32 v54, 0x80, v18
	v_or_b32_e32 v18, s12, v20
	v_mov_b32_e32 v19, s13
	s_lshl_b64 s[74:75], s[72:73], 2
	s_lshl_b64 s[76:77], s[72:73], 11
	v_or_b32_e32 v20, s2, v20
	v_mov_b32_e32 v21, s3
	s_waitcnt vmcnt(11)
	v_mov_b64_e32 v[22:23], v[48:49]
	s_waitcnt vmcnt(10)
	v_mov_b64_e32 v[32:33], v[52:53]
	s_waitcnt vmcnt(9)
	v_mov_b64_e32 v[28:29], v[46:47]
	s_waitcnt vmcnt(8)
	v_mov_b64_e32 v[26:27], v[44:45]
	s_waitcnt vmcnt(4)
	v_mov_b64_e32 v[24:25], v[42:43]
	v_mov_b64_e32 v[30:31], v[50:51]
	s_waitcnt vmcnt(3)
	v_mov_b64_e32 v[34:35], v[40:41]
	s_waitcnt vmcnt(2)
	v_mov_b64_e32 v[36:37], v[38:39]
	s_waitcnt vmcnt(0)
	s_branch .LBB0_663
.LBB0_662:
	s_or_b64 exec, exec, s[20:21]
	s_add_u32 s0, s0, s74
	s_addc_u32 s1, s1, s75
	v_lshl_add_u64 v[18:19], v[18:19], 0, s[76:77]
	v_lshl_add_u64 v[20:21], v[20:21], 0, s[76:77]
	s_andn2_b64 vcc, exec, s[36:37]
	s_waitcnt vmcnt(4)
	v_mov_b64_e32 v[44:45], v[26:27]
	v_mov_b64_e32 v[46:47], v[28:29]
	v_mov_b64_e32 v[50:51], v[30:31]
	v_mov_b64_e32 v[52:53], v[32:33]
	v_mov_b64_e32 v[48:49], v[22:23]
	v_mov_b64_e32 v[42:43], v[24:25]
	v_mov_b64_e32 v[40:41], v[34:35]
	s_waitcnt lgkmcnt(0)
	v_mov_b64_e32 v[38:39], v[36:37]
	s_cbranch_vccz .LBB0_667

; __device__ __forceinline__ unsigned pk2(float lo, float hi) { return f2bf(lo) | (f2bf(hi) << 16); }
; __device__ __forceinline__ float wave_sum(float v, int lane) { v = sum16(v); v += bperm_xor(v, lane, 16); v += bperm_xor(v, lane, 32); return v; }
; __device__ __forceinline__ void rownorm_pass(int lane, int gw, int NGW, bf16* XB, const bf16* MB, const float* gpost, float* RS, float* OUT) {
;     ...
;         f32x4 v[4], mm[4]; float ss = 0.f;
; #pragma unroll
;         for (int j = 0; j < 4; ++j) { mm[j] = (f32x4){bflo(w[j].x), bfhi(w[j].x), bflo(w[j].y), bfhi(w[j].y)}; v[j] = (f32x4){bflo(xw[j].x), bfhi(xw[j].x), bflo(xw[j].y), bfhi(xw[j].y)};
;             ss += (mm[j].x * mm[j].x + mm[j].y * mm[j].y) + (mm[j].z * mm[j].z + mm[j].w * mm[j].w); }
;         const float r = __builtin_amdgcn_rsqf(wave_sum(ss, lane) * (1.f / DMODEL) + EPSN);
;         float s2 = 0.f;
; #pragma unroll
;         for (int j = 0; j < 4; ++j) { v[j] = v[j] + (mm[j] * r) * gp[j]; s2 += (v[j].x * v[j].x + v[j].y * v[j].y) + (v[j].z * v[j].z + v[j].w * v[j].w); }
;         if (OUT) {
; #pragma unroll
;             for (int j = 0; j < 4; ++j) *(f32x4*)(OUT + (size_t)row * DMODEL + 4 * lane + 256 * j) = v[j];
;         } else {
; #pragma unroll
;             for (int j = 0; j < 4; ++j) { v2u q; q.x = pk2(v[j].x, v[j].y); q.y = pk2(v[j].z, v[j].w); *(v2u*)(XB + (size_t)row * DMODEL + 4 * lane + 256 * j) = q; }
;         }
;         if (RS) { const float r2 = __builtin_amdgcn_rsqf(wave_sum(s2, lane) * (1.f / DMODEL) + EPSN); if (lane == 0) RS[row] = r2; }
;         row = nrow;
.LBB0_665:
	v_lshlrev_b32_e32 v57, 16, v53
	v_lshlrev_b32_e32 v56, 16, v52
	v_and_b32_e32 v53, 0xffff0000, v53
	v_and_b32_e32 v52, 0xffff0000, v52
	v_pk_mul_f32 v[60:61], v[52:53], v[52:53]
	v_lshlrev_b32_e32 v63, 16, v51
	v_pk_fma_f32 v[60:61], v[56:57], v[56:57], v[60:61]
	v_lshlrev_b32_e32 v62, 16, v50
	v_and_b32_e32 v51, 0xffff0000, v51
	v_and_b32_e32 v50, 0xffff0000, v50
	v_pk_add_f32 v[60:61], v[60:61], v[60:61] op_sel_hi:[0,1]
	v_pk_mul_f32 v[66:67], v[50:51], v[50:51]
	v_lshlrev_b32_e32 v68, 16, v46
	v_and_b32_e32 v69, 0xffff0000, v46
	v_lshlrev_b32_e32 v46, 16, v47
	v_lshlrev_b32_e32 v70, 16, v44
	v_pk_fma_f32 v[66:67], v[62:63], v[62:63], v[66:67]
	v_and_b32_e32 v47, 0xffff0000, v47
	v_mul_f32_e32 v71, v68, v68
	v_mul_f32_e32 v73, v69, v69
	v_mul_f32_e32 v60, v46, v46
	v_mov_b32_e32 v72, v70
	v_pk_add_f32 v[66:67], v[66:67], v[66:67] op_sel_hi:[0,1]
	v_pk_fma_f32 v[74:75], v[46:47], v[46:47], v[60:61] op_sel_hi:[1,1,0]
	v_and_b32_e32 v55, 0xffff0000, v44
	v_lshlrev_b32_e32 v44, 16, v45
	v_and_b32_e32 v45, 0xffff0000, v45
	v_pk_add_f32 v[72:73], v[70:71], v[72:73]
	v_mul_f32_e32 v74, v55, v55
	v_mul_f32_e32 v66, v44, v44
	v_mul_f32_e32 v60, v45, v45
	v_mul_f32_e32 v76, v70, v70
	v_mov_b32_e32 v77, v73
	v_pk_add_f32 v[72:73], v[76:77], v[74:75]
	v_pk_add_f32 v[60:61], v[66:67], v[60:61]
	v_mov_b32_e32 v74, v56
	v_pk_add_f32 v[60:61], v[72:73], v[60:61]
	v_mov_b32_e32 v75, v52
	v_add_f32_e32 v60, v60, v61
	v_mov_b32_e32 v52, v57
	v_lshlrev_b32_e32 v58, 16, v48
	v_add_f32_dpp v60, v60, v60 quad_perm:[1,0,3,2] row_mask:0xf bank_mask:0xf bound_ctrl:1
	v_and_b32_e32 v59, 0xffff0000, v48
	v_lshlrev_b32_e32 v48, 16, v49
	v_add_f32_dpp v60, v60, v60 quad_perm:[2,3,0,1] row_mask:0xf bank_mask:0xf bound_ctrl:1
	v_and_b32_e32 v49, 0xffff0000, v49
	v_lshlrev_b32_e32 v64, 16, v42
	v_add_f32_dpp v60, v60, v60 row_half_mirror row_mask:0xf bank_mask:0xf bound_ctrl:1
	v_and_b32_e32 v65, 0xffff0000, v42
	v_lshlrev_b32_e32 v42, 16, v43
	v_add_f32_dpp v66, v60, v60 row_mirror row_mask:0xf bank_mask:0xf bound_ctrl:1
	ds_bpermute_b32 v67, v1, v66
	v_and_b32_e32 v43, 0xffff0000, v43
	v_lshlrev_b32_e32 v60, 16, v40
	v_and_b32_e32 v61, 0xffff0000, v40
	v_lshlrev_b32_e32 v40, 16, v41
	s_waitcnt lgkmcnt(0)
	v_add_f32_e32 v71, v66, v67
	ds_bpermute_b32 v72, v54, v71
	v_and_b32_e32 v41, 0xffff0000, v41
	v_lshlrev_b32_e32 v66, 16, v38
	v_and_b32_e32 v67, 0xffff0000, v38
	v_lshlrev_b32_e32 v38, 16, v39
	s_waitcnt lgkmcnt(0)
	v_add_f32_e32 v71, v71, v72
	v_fmamk_f32 v71, v71, 0x3a800000, v241
	v_rsq_f32_e32 v72, v71
	v_mov_b32_e32 v71, v55
	v_and_b32_e32 v39, 0xffff0000, v39
	s_mov_b32 s2, 0x35200000
	v_pk_mul_f32 v[74:75], v[72:73], v[74:75] op_sel_hi:[0,1]
	v_pk_mul_f32 v[52:53], v[72:73], v[52:53] op_sel_hi:[0,1]
	v_pk_fma_f32 v[48:49], v[4:5], v[52:53], v[48:49]
	v_pk_fma_f32 v[52:53], v[2:3], v[74:75], v[58:59]
	v_mul_f32_e32 v57, v49, v49
	v_mul_f32_e32 v56, v53, v53
	v_fmac_f32_e32 v56, v52, v52
	v_fmac_f32_e32 v57, v48, v48
	v_add_f32_e32 v58, v56, v57
	v_mov_b32_e32 v56, v62
	v_mov_b32_e32 v57, v50
	v_mov_b32_e32 v50, v63
	v_pk_mul_f32 v[56:57], v[72:73], v[56:57] op_sel_hi:[0,1]
	v_pk_mul_f32 v[50:51], v[72:73], v[50:51] op_sel_hi:[0,1]
	v_pk_fma_f32 v[42:43], v[8:9], v[50:51], v[42:43]
	v_pk_fma_f32 v[50:51], v[6:7], v[56:57], v[64:65]
	v_mul_f32_e32 v57, v43, v43
	v_mul_f32_e32 v56, v51, v51
	v_fmac_f32_e32 v56, v50, v50
	v_fmac_f32_e32 v57, v42, v42
	v_add_f32_e32 v56, v56, v57
	v_add_f32_e32 v58, v58, v56
	v_pk_mul_f32 v[56:57], v[68:69], v[72:73] op_sel_hi:[1,0]
	v_pk_mul_f32 v[46:47], v[46:47], v[72:73] op_sel_hi:[1,0]
	v_pk_mul_f32 v[44:45], v[44:45], v[72:73] op_sel_hi:[1,0]
	v_pk_fma_f32 v[40:41], v[12:13], v[46:47], v[40:41]
	v_pk_fma_f32 v[46:47], v[10:11], v[56:57], v[60:61]
	v_mul_f32_e32 v57, v41, v41
	v_mul_f32_e32 v56, v47, v47
	v_fmac_f32_e32 v56, v46, v46
	v_fmac_f32_e32 v57, v40, v40
	v_add_f32_e32 v56, v56, v57
	v_add_f32_e32 v58, v56, v58
	v_pk_mul_f32 v[56:57], v[70:71], v[72:73] op_sel_hi:[1,0]
	v_pk_fma_f32 v[44:45], v[16:17], v[44:45], v[38:39]
	v_pk_fma_f32 v[38:39], v[14:15], v[56:57], v[66:67]
	v_mul_f32_e32 v56, v45, v45
	v_mul_f32_e32 v55, v39, v39
	v_fmac_f32_e32 v55, v38, v38
	v_fmac_f32_e32 v56, v44, v44
	v_add_f32_e32 v55, v55, v56
	v_add_f32_e32 v55, v55, v58
	v_bfe_u32 v58, v52, 16, 1
	v_add3_u32 v52, v52, v58, s34
	v_bfe_u32 v58, v53, 16, 1
	v_lshrrev_b32_e32 v52, 16, v52
	v_add3_u32 v53, v53, v58, s34
	v_and_or_b32 v52, v53, s31, v52
	v_bfe_u32 v53, v48, 16, 1
	v_add3_u32 v48, v48, v53, s34
	v_bfe_u32 v53, v49, 16, 1
	v_lshl_add_u64 v[56:57], s[10:11], 0, v[18:19]
	v_lshrrev_b32_e32 v48, 16, v48
	v_add3_u32 v49, v49, v53, s34
	v_and_or_b32 v53, v49, s31, v48
	v_add_co_u32_e32 v48, vcc, s2, v56
	s_nop 1
	v_addc_co_u32_e32 v49, vcc, 0, v57, vcc
	global_store_dwordx2 v[48:49], v[52:53], off
	v_bfe_u32 v52, v50, 16, 1
	v_add3_u32 v50, v50, v52, s34
	v_bfe_u32 v52, v51, 16, 1
	v_lshrrev_b32_e32 v50, 16, v50
	v_add3_u32 v51, v51, v52, s34
	v_and_or_b32 v50, v51, s31, v50
	v_bfe_u32 v51, v42, 16, 1
	v_add3_u32 v42, v42, v51, s34
	v_bfe_u32 v51, v43, 16, 1
	v_lshrrev_b32_e32 v42, 16, v42
	v_add3_u32 v43, v43, v51, s34
	v_and_or_b32 v51, v43, s31, v42
	v_bfe_u32 v42, v46, 16, 1
	v_add3_u32 v42, v46, v42, s34
	v_bfe_u32 v43, v47, 16, 1
	v_lshrrev_b32_e32 v42, 16, v42
	v_add3_u32 v43, v47, v43, s34
	v_and_or_b32 v42, v43, s31, v42
	v_bfe_u32 v43, v40, 16, 1
	v_add3_u32 v40, v40, v43, s34
	v_bfe_u32 v43, v41, 16, 1
	v_lshrrev_b32_e32 v40, 16, v40
	v_add3_u32 v41, v41, v43, s34
	v_and_or_b32 v43, v41, s31, v40
	v_bfe_u32 v40, v38, 16, 1
	v_add3_u32 v38, v38, v40, s34
	v_bfe_u32 v40, v39, 16, 1
	v_add3_u32 v39, v39, v40, s34
	global_store_dwordx2 v[48:49], v[42:43], off offset:1024
	v_add_f32_dpp v40, v55, v55 quad_perm:[1,0,3,2] row_mask:0xf bank_mask:0xf bound_ctrl:1
	v_lshrrev_b32_e32 v38, 16, v38
	global_store_dwordx2 v[48:49], v[50:51], off offset:512
	v_add_f32_dpp v40, v40, v40 quad_perm:[2,3,0,1] row_mask:0xf bank_mask:0xf bound_ctrl:1
	s_nop 1
	v_add_f32_dpp v40, v40, v40 row_half_mirror row_mask:0xf bank_mask:0xf bound_ctrl:1
	s_nop 1
	v_add_f32_dpp v41, v40, v40 row_mirror row_mask:0xf bank_mask:0xf bound_ctrl:1
	ds_bpermute_b32 v42, v1, v41
	v_and_or_b32 v40, v39, s31, v38
	v_bfe_u32 v38, v44, 16, 1
	v_add3_u32 v38, v44, v38, s34
	v_lshrrev_b32_e32 v43, 16, v38
	s_waitcnt lgkmcnt(0)
	v_add_f32_e32 v38, v41, v42
	ds_bpermute_b32 v39, v54, v38
	v_bfe_u32 v41, v45, 16, 1
	v_add3_u32 v41, v45, v41, s34
	v_and_or_b32 v41, v41, s31, v43
	global_store_dwordx2 v[48:49], v[40:41], off offset:1536
	s_and_saveexec_b64 s[20:21], s[6:7]
	s_cbranch_execz .LBB0_662
	s_waitcnt lgkmcnt(0)
	v_add_f32_e32 v38, v38, v39
	v_fmamk_f32 v38, v38, 0x3a800000, v241
	v_rsq_f32_e32 v38, v38
	s_add_u32 s2, s10, s0
	s_addc_u32 s3, s11, s1
	global_store_dword v0, v38, s[2:3]
	s_branch .LBB0_662

; #define ARG_OUT() ((float*)karg<120>())
; #define ARG_WS() ((unsigned char*)karg<128>())
; __device__ __forceinline__ void rownorm_pass(int lane, int gw, int NGW, bf16* XB, const bf16* MB, const float* gpost, float* RS, float* OUT) {
;     f32x4 gp[4];
; #pragma unroll
;     for (int j = 0; j < 4; ++j) gp[j] = *(const f32x4*)(gpost + 4 * lane + 256 * j);
;     v2u nx[4], nm[4];
;     int row = gw;
;     if (row < MTOK) {
; #pragma unroll
;         for (int j = 0; j < 4; ++j) { nx[j] = *(const v2u*)(XB + (size_t)row * DMODEL + 4 * lane + 256 * j); nm[j] = __builtin_nontemporal_load((const v2u*)(MB + (size_t)row * DMODEL + 4 * lane + 256 * j)); }
;     }
;     while (row < MTOK) {
;         v2u xw[4], w[4];
; #pragma unroll
;         for (int j = 0; j < 4; ++j) { xw[j] = nx[j]; w[j] = nm[j]; }
;         const int nrow = row + NGW;
;         if (nrow < MTOK) {
; #pragma unroll
;             for (int j = 0; j < 4; ++j) { nx[j] = *(const v2u*)(XB + (size_t)nrow * DMODEL + 4 * lane + 256 * j); nm[j] = __builtin_nontemporal_load((const v2u*)(MB + (size_t)nrow * DMODEL + 4 * lane + 256 * j)); }
;         }
; __global__ void __launch_bounds__(NWAVES * 64, 2) encoder_fwd(Args args) {
;     ...
;             PHASE_IDS();
;             unsigned char* const ws = ARG_WS(); bf16* const XB = (bf16*)(ws + WS_XB); const bf16* const MB = (const bf16*)(ws + WS_OB);
;             float* const OUT = (l == 3) ? ARG_OUT() : nullptr; float* const RS = (l < 3) ? (float*)(ws + WS_RS) : nullptr;
;             const float* const gpost = ARG_IN(14) + l * DMODEL;
;             rownorm_pass(lane, gw, NGW, XB, MB, gpost, RS, OUT);
.LBB0_865:
	s_ashr_i32 s3, s1, 6
	s_lshl_b32 s2, s2, 3
	s_add_i32 s10, s2, s3
	s_cmp_gt_i32 s10, 0x13fff
	s_load_dwordx2 s[4:5], s[4:5], 0x70
	s_waitcnt lgkmcnt(0)
	s_cbranch_scc1 .LBB0_878
	v_readlane_b32 s12, v255, 3
	v_readlane_b32 s13, v255, 4
	s_lshl_b64 s[12:13], s[12:13], 2
	s_add_u32 s4, s4, s12
	s_addc_u32 s5, s5, s13
	s_ashr_i32 s11, s10, 31
	s_lshl_b32 s72, s0, 3
	s_lshl_b64 s[0:1], s[10:11], 11
	v_and_b32_e32 v1, 63, v1
	s_add_u32 s12, s8, s0
	s_addc_u32 s13, s9, s1
	v_lshlrev_b32_e32 v38, 3, v1
	v_mov_b32_e32 v39, v0
	v_lshl_add_u64 v[10:11], s[12:13], 0, v[38:39]
	s_mov_b64 s[12:13], 0xfa00000
	v_lshl_add_u64 v[12:13], v[10:11], 0, s[12:13]
	s_mov_b32 s12, 0x35200000
	v_add_co_u32_e32 v2, vcc, s12, v10
	s_mov_b32 s12, 0xfa00000
	s_nop 0
	v_addc_co_u32_e32 v3, vcc, 0, v11, vcc
	v_add_co_u32_e32 v4, vcc, s12, v10
	v_lshlrev_b32_e32 v36, 4, v1
	s_nop 0
	v_addc_co_u32_e32 v5, vcc, 0, v11, vcc
	global_load_dwordx2 v[28:29], v[2:3], off
	global_load_dwordx2 v[32:33], v[4:5], off nt
	global_load_dwordx2 v[26:27], v[12:13], off offset:1024 nt
	global_load_dwordx2 v[24:25], v[12:13], off offset:1536 nt
	s_nop 0
	global_load_dwordx4 v[2:5], v36, s[4:5]
	global_load_dwordx4 v[6:9], v36, s[4:5] offset:1024
	global_load_dwordx2 v[30:31], v[12:13], off offset:512 nt
	s_mov_b64 s[12:13], 0x35200000
	v_lshl_add_u64 v[10:11], v[10:11], 0, s[12:13]
	global_load_dwordx2 v[22:23], v[10:11], off offset:512
	global_load_dwordx2 v[20:21], v[10:11], off offset:1024
	global_load_dwordx2 v[18:19], v[10:11], off offset:1536
	s_nop 0
	global_load_dwordx4 v[10:13], v36, s[4:5] offset:2048
	global_load_dwordx4 v[14:17], v36, s[4:5] offset:3072
	s_cmp_lg_u64 s[36:37], 0
	v_lshlrev_b32_e32 v34, 2, v1
	s_cselect_b64 s[74:75], -1, 0
	s_ashr_i32 s73, s72, 31
	v_cmp_eq_u32_e64 s[4:5], 0, v1
	v_xor_b32_e32 v1, 64, v34
	v_xor_b32_e32 v56, 0x80, v34
	v_or_b32_e32 v34, s0, v38
	v_mov_b32_e32 v35, s1
	s_lshl_b64 s[0:1], s[10:11], 2
	s_lshl_b64 s[76:77], s[72:73], 11
	s_add_u32 s0, s0, 0xa0000
	s_addc_u32 s1, s1, 0
	s_lshl_b64 s[78:79], s[72:73], 2
	s_lshl_b64 s[12:13], s[10:11], 12
	s_add_u32 s12, s36, s12
	s_addc_u32 s13, s37, s13
	s_add_i32 s3, s3, s72
	s_add_i32 s2, s3, s2
	s_ashr_i32 s3, s2, 31
	v_mov_b32_e32 v37, v0
	s_lshl_b64 s[2:3], s[2:3], 11
	s_lshl_b64 s[80:81], s[72:73], 12
	v_lshl_add_u64 v[36:37], s[12:13], 0, v[36:37]
	v_or_b32_e32 v38, s2, v38
	v_mov_b32_e32 v39, s3
	s_waitcnt vmcnt(11)
	v_mov_b64_e32 v[40:41], v[28:29]
	s_waitcnt vmcnt(10)
	v_mov_b64_e32 v[50:51], v[32:33]
	s_waitcnt vmcnt(9)
	v_mov_b64_e32 v[46:47], v[26:27]
	s_waitcnt vmcnt(8)
	v_mov_b64_e32 v[44:45], v[24:25]
	s_waitcnt vmcnt(4)
	v_mov_b64_e32 v[42:43], v[22:23]
	v_mov_b64_e32 v[48:49], v[30:31]
	s_waitcnt vmcnt(3)
	v_mov_b64_e32 v[52:53], v[20:21]
	s_waitcnt vmcnt(2)
	v_mov_b64_e32 v[54:55], v[18:19]
	s_waitcnt vmcnt(0)
	s_branch .LBB0_869

; __device__ __forceinline__ void rownorm_pass(int lane, int gw, int NGW, bf16* XB, const bf16* MB, const float* gpost, float* RS, float* OUT) {
;     ...
;     while (row < MTOK) {
;         v2u xw[4], w[4];
; #pragma unroll
;         for (int j = 0; j < 4; ++j) { xw[j] = nx[j]; w[j] = nm[j]; }
;         const int nrow = row + NGW;
;         if (nrow < MTOK) {
.LBB0_868:
	s_add_u32 s0, s0, s78
	v_lshl_add_u64 v[34:35], v[34:35], 0, s[76:77]
	s_addc_u32 s1, s1, s79
	v_lshl_add_u64 v[36:37], v[36:37], 0, s[80:81]
	v_lshl_add_u64 v[38:39], v[38:39], 0, s[76:77]
	s_andn2_b64 vcc, exec, s[82:83]
	s_waitcnt vmcnt(4)
	v_mov_b64_e32 v[24:25], v[44:45]
	v_mov_b64_e32 v[26:27], v[46:47]
	v_mov_b64_e32 v[30:31], v[48:49]
	v_mov_b64_e32 v[32:33], v[50:51]
	v_mov_b64_e32 v[28:29], v[40:41]
	v_mov_b64_e32 v[22:23], v[42:43]
	v_mov_b64_e32 v[20:21], v[52:53]
	s_waitcnt lgkmcnt(0)
	v_mov_b64_e32 v[18:19], v[54:55]
	s_cbranch_vccz .LBB0_878

; __device__ __forceinline__ float wave_sum(float v, int lane) { v = sum16(v); v += bperm_xor(v, lane, 16); v += bperm_xor(v, lane, 32); return v; }
; __device__ __forceinline__ void rownorm_pass(int lane, int gw, int NGW, bf16* XB, const bf16* MB, const float* gpost, float* RS, float* OUT) {
;     ...
;         f32x4 v[4], mm[4]; float ss = 0.f;
; #pragma unroll
;         for (int j = 0; j < 4; ++j) { mm[j] = (f32x4){bflo(w[j].x), bfhi(w[j].x), bflo(w[j].y), bfhi(w[j].y)}; v[j] = (f32x4){bflo(xw[j].x), bfhi(xw[j].x), bflo(xw[j].y), bfhi(xw[j].y)};
;             ss += (mm[j].x * mm[j].x + mm[j].y * mm[j].y) + (mm[j].z * mm[j].z + mm[j].w * mm[j].w); }
;         const float r = __builtin_amdgcn_rsqf(wave_sum(ss, lane) * (1.f / DMODEL) + EPSN);
;         float s2 = 0.f;
; #pragma unroll
;         for (int j = 0; j < 4; ++j) { v[j] = v[j] + (mm[j] * r) * gp[j]; s2 += (v[j].x * v[j].x + v[j].y * v[j].y) + (v[j].z * v[j].z + v[j].w * v[j].w); }
;         if (OUT) {
; #pragma unroll
;             for (int j = 0; j < 4; ++j) *(f32x4*)(OUT + (size_t)row * DMODEL + 4 * lane + 256 * j) = v[j];
.LBB0_871:
	v_lshlrev_b32_e32 v59, 16, v33
	v_lshlrev_b32_e32 v58, 16, v32
	v_and_b32_e32 v33, 0xffff0000, v33
	v_and_b32_e32 v32, 0xffff0000, v32
	v_pk_mul_f32 v[62:63], v[32:33], v[32:33]
	v_lshlrev_b32_e32 v65, 16, v31
	v_pk_fma_f32 v[62:63], v[58:59], v[58:59], v[62:63]
	v_lshlrev_b32_e32 v64, 16, v30
	v_and_b32_e32 v31, 0xffff0000, v31
	v_and_b32_e32 v30, 0xffff0000, v30
	v_pk_add_f32 v[62:63], v[62:63], v[62:63] op_sel_hi:[0,1]
	v_pk_mul_f32 v[68:69], v[30:31], v[30:31]
	v_lshlrev_b32_e32 v70, 16, v26
	v_and_b32_e32 v71, 0xffff0000, v26
	v_lshlrev_b32_e32 v26, 16, v27
	v_lshlrev_b32_e32 v72, 16, v24
	v_pk_fma_f32 v[68:69], v[64:65], v[64:65], v[68:69]
	v_and_b32_e32 v27, 0xffff0000, v27
	v_mul_f32_e32 v73, v70, v70
	v_mul_f32_e32 v75, v71, v71
	v_mul_f32_e32 v62, v26, v26
	v_mov_b32_e32 v74, v72
	v_pk_add_f32 v[68:69], v[68:69], v[68:69] op_sel_hi:[0,1]
	v_pk_fma_f32 v[76:77], v[26:27], v[26:27], v[62:63] op_sel_hi:[1,1,0]
	v_and_b32_e32 v57, 0xffff0000, v24
	v_lshlrev_b32_e32 v78, 16, v25
	v_and_b32_e32 v79, 0xffff0000, v25
	v_pk_add_f32 v[74:75], v[72:73], v[74:75]
	v_mul_f32_e32 v76, v57, v57
	v_mul_f32_e32 v68, v78, v78
	v_mul_f32_e32 v62, v79, v79
	v_mul_f32_e32 v24, v72, v72
	v_mov_b32_e32 v25, v75
	v_pk_add_f32 v[24:25], v[24:25], v[76:77]
	v_pk_add_f32 v[62:63], v[68:69], v[62:63]
	v_lshlrev_b32_e32 v74, 16, v18
	v_pk_add_f32 v[24:25], v[24:25], v[62:63]
	v_lshlrev_b32_e32 v62, 16, v20
	v_add_f32_e32 v24, v24, v25
	v_and_b32_e32 v63, 0xffff0000, v20
	v_and_b32_e32 v75, 0xffff0000, v18
	v_add_f32_dpp v24, v24, v24 quad_perm:[1,0,3,2] row_mask:0xf bank_mask:0xf bound_ctrl:1
	v_lshlrev_b32_e32 v76, 16, v19
	v_and_b32_e32 v77, 0xffff0000, v19
	v_add_f32_dpp v24, v24, v24 quad_perm:[2,3,0,1] row_mask:0xf bank_mask:0xf bound_ctrl:1
	v_mov_b32_e32 v19, v32
	v_mov_b32_e32 v32, v59
	v_add_f32_dpp v24, v24, v24 row_half_mirror row_mask:0xf bank_mask:0xf bound_ctrl:1
	v_lshlrev_b32_e32 v60, 16, v28
	v_and_b32_e32 v61, 0xffff0000, v28
	v_add_f32_dpp v24, v24, v24 row_mirror row_mask:0xf bank_mask:0xf bound_ctrl:1
	ds_bpermute_b32 v25, v1, v24
	v_lshlrev_b32_e32 v28, 16, v29
	v_and_b32_e32 v29, 0xffff0000, v29
	v_lshlrev_b32_e32 v68, 16, v21
	v_and_b32_e32 v69, 0xffff0000, v21
	s_waitcnt lgkmcnt(0)
	v_add_f32_e32 v20, v24, v25
	ds_bpermute_b32 v24, v56, v20
	v_mov_b32_e32 v25, v30
	v_mov_b32_e32 v30, v65
	v_lshlrev_b32_e32 v66, 16, v22
	v_and_b32_e32 v67, 0xffff0000, v22
	s_waitcnt lgkmcnt(0)
	v_add_f32_e32 v18, v20, v24
	v_fmamk_f32 v18, v18, 0x3a800000, v241
	v_rsq_f32_e32 v80, v18
	v_mov_b32_e32 v24, v64
	v_lshlrev_b32_e32 v22, 16, v23
	v_and_b32_e32 v23, 0xffff0000, v23
	v_pk_mul_f32 v[20:21], v[80:81], v[32:33] op_sel_hi:[0,1]
	v_mov_b32_e32 v18, v58
	v_pk_fma_f32 v[20:21], v[4:5], v[20:21], v[28:29]
	v_pk_mul_f32 v[28:29], v[80:81], v[24:25] op_sel_hi:[0,1]
	v_pk_mul_f32 v[24:25], v[80:81], v[30:31] op_sel_hi:[0,1]
	v_pk_mul_f32 v[30:31], v[70:71], v[80:81] op_sel_hi:[1,0]
	v_pk_mul_f32 v[26:27], v[26:27], v[80:81] op_sel_hi:[1,0]
	v_mov_b32_e32 v73, v57
	v_pk_mul_f32 v[18:19], v[80:81], v[18:19] op_sel_hi:[0,1]
	v_pk_fma_f32 v[24:25], v[8:9], v[24:25], v[22:23]
	v_pk_fma_f32 v[22:23], v[6:7], v[28:29], v[66:67]
	v_pk_fma_f32 v[28:29], v[12:13], v[26:27], v[68:69]
	v_pk_fma_f32 v[26:27], v[10:11], v[30:31], v[62:63]
	v_pk_mul_f32 v[30:31], v[72:73], v[80:81] op_sel_hi:[1,0]
	v_pk_mul_f32 v[32:33], v[78:79], v[80:81] op_sel_hi:[1,0]
	v_pk_fma_f32 v[18:19], v[2:3], v[18:19], v[60:61]
	v_pk_fma_f32 v[32:33], v[16:17], v[32:33], v[76:77]
	s_andn2_b64 vcc, exec, s[74:75]
	v_pk_fma_f32 v[30:31], v[14:15], v[30:31], v[74:75]
	s_cbranch_vccnz .LBB0_877
	global_store_dwordx4 v[36:37], v[18:21], off
	global_store_dwordx4 v[36:37], v[22:25], off offset:1024
	global_store_dwordx4 v[36:37], v[26:29], off offset:2048
	global_store_dwordx4 v[36:37], v[30:33], off offset:3072
	s_cbranch_execnz .LBB0_874
